# phase 3 (token shift / norms / rope prep) rewritten by hand: invariant parameters hoisted, packed fp32 math, coalesced 16B accesses
# speedup vs baseline: 1.0737x; 1.0288x over previous
; #define UNPACK8(v, f) do { f[0]=lo16(v.x); f[1]=hi16(v.x); f[2]=lo16(v.y); f[3]=hi16(v.y); f[4]=lo16(v.z); f[5]=hi16(v.z); f[6]=lo16(v.w); f[7]=hi16(v.w); } while (0)
; DI void phase3(const Params& P) {
;   const int lane = threadIdx.x & 63, gw = blockIdx.x * 8 + (threadIdx.x >> 6), nw = gridDim.x * 8;
;   const bf16_t* __restrict__ USH = (const bf16_t*)(P.ws + OFF_USH);
;   const bf16_t* __restrict__ UMLA = (const bf16_t*)(P.ws + OFF_UMLA);
;   for (int m = gw; m < T_ALL; m += nw) {
;     int b, t, len, kpos;
;     if (m < T_LAT) { b = m >> 13; t = m & 8191; len = SEQ; kpos = t; } else { b = (m - T_LAT) >> 8; t = (m - T_LAT) & 255; len = CTXL; kpos = SEQ + t; }
;     const bool hasp = t > 0, hasn = t < len - 1;
;     const uint4 z4 = make_uint4(0, 0, 0, 0);
; #pragma unroll
;     for (int arr = 0; arr < 3; ++arr) {
;       const int col = arr * 512 + lane * 8;
;       uint4 cu = *(const uint4*)(USH + (size_t)m * 1792 + col);
;       uint4 pu = hasp ? *(const uint4*)(USH + (size_t)(m - 1) * 1792 + col) : z4;
;       uint4 nu = hasn ? *(const uint4*)(USH + (size_t)(m + 1) * 1792 + col) : z4;
;       float c8[8], p8[8], n8[8], o8[8]; UNPACK8(cu, c8); UNPACK8(pu, p8); UNPACK8(nu, n8);
; #pragma unroll
;       for (int j = 0; j < 8; ++j) { float mu0 = P.shift_mu[col + j], mu1 = P.shift_mu[1792 + col + j]; o8[j] = c8[j] + mu0 * (p8[j] - c8[j]) + mu1 * (n8[j] - c8[j]); }
.LBB0_604:
	s_cmp_lt_i32 s96, 4
	s_cselect_b64 s[0:1], -1, 0
	s_cmp_gt_i32 s97, 3
	s_cselect_b64 s[2:3], -1, 0
	s_and_b64 s[0:1], s[0:1], s[2:3]
	s_andn2_b64 vcc, exec, s[0:1]
	s_cbranch_vccnz .LBB0_752
	s_load_dword s0, s[78:79], 0xd8
	v_lshl_add_u32 v0, s76, 3, v209
	s_movk_i32 s1, 0x4200
	v_cmp_gt_i32_e32 vcc, s1, v0
	s_and_saveexec_b64 s[20:21], vcc
	s_cbranch_execz .LBB0_698
	s_waitcnt lgkmcnt(0)
	s_lshl_b32 s11, s0, 3
	v_readfirstlane_b32 s10, v0
	v_and_b32_e32 v1, 63, v208
	v_lshlrev_b32_e32 v2, 4, v1
	v_lshlrev_b32_e32 v3, 3, v1
	v_and_b32_e32 v4, 3, v208
	v_lshlrev_b32_e32 v4, 4, v4
	v_lshlrev_b32_e32 v5, 5, v1
	v_add_u32_e32 v7, 0x800, v5
	v_add_u32_e32 v8, 0x1000, v5
	v_add_u32_e32 v9, 0x1800, v2
	v_and_b32_e32 v6, 1, v208
	v_and_b32_e32 v10, 2, v208
	v_cmp_gt_u32_e64 s[44:45], 48, v1
	v_cmp_gt_u32_e64 s[46:47], 32, v1
	v_cmp_gt_u32_e64 s[48:49], 4, v1
	v_cmp_eq_u32_e64 s[50:51], 0, v6
	v_readlane_b32 s52, v243, 2
	v_readlane_b32 s53, v243, 3
	v_readlane_b32 s54, v243, 12
	v_readlane_b32 s55, v243, 13
	v_readlane_b32 s56, v243, 22
	v_readlane_b32 s57, v243, 23
	v_readlane_b32 s58, v243, 24
	v_readlane_b32 s59, v243, 25
	s_nop 4
	s_add_u32 s40, s52, 0x1c00
	s_addc_u32 s41, s53, 0
	global_load_dwordx4 v[16:19], v5, s[52:53]
	global_load_dwordx4 v[20:23], v5, s[52:53] offset:16
	global_load_dwordx4 v[40:43], v5, s[40:41]
	global_load_dwordx4 v[44:47], v5, s[40:41] offset:16
	global_load_dwordx4 v[24:27], v7, s[52:53]
	global_load_dwordx4 v[28:31], v7, s[52:53] offset:16
	global_load_dwordx4 v[48:51], v7, s[40:41]
	global_load_dwordx4 v[52:55], v7, s[40:41] offset:16
	global_load_dwordx4 v[32:35], v8, s[52:53]
	global_load_dwordx4 v[36:39], v8, s[52:53] offset:16
	global_load_dwordx4 v[56:59], v8, s[40:41]
	global_load_dwordx4 v[60:63], v8, s[40:41] offset:16
	global_load_dwordx4 v[88:91], v9, s[52:53]
	global_load_dwordx4 v[92:95], v9, s[40:41]
	global_load_dwordx4 v[100:103], v5, s[54:55]
	global_load_dwordx4 v[104:107], v5, s[54:55] offset:16
	v_mov_b32_e32 v108, 0
	v_mov_b32_e32 v109, 0
	v_mov_b32_e32 v110, 0
	v_mov_b32_e32 v111, 0
	v_mov_b32_e32 v112, 0
	v_mov_b32_e32 v113, 0
	v_mov_b32_e32 v114, 0
	v_mov_b32_e32 v115, 0
	v_mov_b32_e32 v116, 0
	v_mov_b32_e32 v117, 0
	v_mov_b32_e32 v118, 0
	v_mov_b32_e32 v119, 0
	v_mov_b32_e32 v120, 0
	v_mov_b32_e32 v121, 0
	v_mov_b32_e32 v122, 0
	v_mov_b32_e32 v123, 0
	s_mov_b64 s[32:33], exec
	s_and_b64 exec, exec, s[44:45]
	global_load_dwordx4 v[108:111], v5, s[56:57]
	global_load_dwordx4 v[112:115], v5, s[56:57] offset:16
	s_and_b64 exec, exec, s[46:47]
	global_load_dwordx4 v[116:119], v5, s[58:59]
	global_load_dwordx4 v[120:123], v5, s[58:59] offset:16
	s_mov_b64 exec, s[32:33]
	v_cmp_eq_u32_e64 s[56:57], 0, v10
	s_waitcnt vmcnt(0)
.Lp3_loop:
	s_sub_u32 s1, s10, 0x4000
	s_lshr_b32 s2, s10, 13
	s_and_b32 s3, s10, 0x1fff
	s_lshr_b32 s4, s1, 8
	s_and_b32 s5, s1, 0xff
	s_add_u32 s9, s5, 0x2000
	s_movk_i32 s8, 0xff
	s_cmp_lt_u32 s10, 0x4000
	s_cselect_b32 s6, s2, s4
	s_cselect_b32 s7, s3, s5
	s_cselect_b32 s8, 0x1fff, s8
	s_cselect_b32 s9, s3, s9
	s_mul_i32 s0, s10, 0xe00
	s_add_u32 s12, s94, s0
	s_addc_u32 s13, s95, 0
	s_add_u32 s12, s12, 0xb00000
	s_addc_u32 s13, s13, 0
	s_sub_u32 s14, s12, 0xe00
	s_subb_u32 s15, s13, 0
	s_add_u32 s16, s12, 0xe00
	s_addc_u32 s17, s13, 0
	s_mul_i32 s0, s10, 0x540
	s_add_u32 s18, s94, s0
	s_addc_u32 s19, s95, 0
	s_add_u32 s18, s18, 0x44c0000
	s_addc_u32 s19, s19, 0
	global_load_dwordx4 v[124:127], v2, s[12:13]
	global_load_dwordx4 v[128:131], v2, s[14:15]
	global_load_dwordx4 v[132:135], v2, s[16:17]
	global_load_dwordx4 v[136:139], v2, s[12:13] offset:1024
	global_load_dwordx4 v[140:143], v2, s[14:15] offset:1024
	global_load_dwordx4 v[144:147], v2, s[16:17] offset:1024
	global_load_dwordx4 v[148:151], v2, s[12:13] offset:2048
	global_load_dwordx4 v[152:155], v2, s[14:15] offset:2048
	global_load_dwordx4 v[156:159], v2, s[16:17] offset:2048
	global_load_dwordx2 v[160:161], v3, s[12:13] offset:3072
	global_load_dwordx2 v[162:163], v3, s[14:15] offset:3072
	global_load_dwordx2 v[164:165], v3, s[16:17] offset:3072
	global_load_dwordx4 v[166:169], v2, s[18:19]
	global_load_dwordx4 v[170:173], v2, s[18:19] offset:768
	global_load_dwordx4 v[174:177], v4, s[18:19] offset:1280
	s_lshl_b32 s0, s10, 10
	s_add_u32 s22, s94, s0
	s_addc_u32 s23, s95, 0
	s_add_u32 s22, s22, 0x7b68000
	s_addc_u32 s23, s23, 0
	s_add_u32 s24, s94, s0
	s_addc_u32 s25, s95, 0
	s_add_u32 s24, s24, 0x8be8000
	s_addc_u32 s25, s25, 0
	s_add_u32 s26, s94, s0
	s_addc_u32 s27, s95, 0
	s_add_u32 s26, s26, 0x9c68000
	s_addc_u32 s27, s27, 0
	s_add_u32 s28, s94, s0
	s_addc_u32 s29, s95, 0
	s_add_u32 s28, s28, 0xace8000
	s_addc_u32 s29, s29, 0
	s_lshl_b32 s0, s10, 9
	s_add_u32 s30, s94, s0
	s_addc_u32 s31, s95, 0
	s_add_u32 s30, s30, 0x6f08000
	s_addc_u32 s31, s31, 0
	s_add_u32 s36, s94, s0
	s_addc_u32 s37, s95, 0
	s_add_u32 s36, s36, 0x66c8000
	s_addc_u32 s37, s37, 0
	s_mul_i32 s0, s10, 0x300
	s_add_u32 s34, s94, s0
	s_addc_u32 s35, s95, 0
	s_add_u32 s34, s34, 0x5a68000
	s_addc_u32 s35, s35, 0
	s_mul_i32 s0, s6, 0x2100
	s_add_u32 s0, s0, s9
	s_lshl_b32 s0, s0, 6
	s_add_u32 s38, s94, s0
	s_addc_u32 s39, s95, 0
	s_add_u32 s38, s38, 0xbd68000
	s_addc_u32 s39, s39, 0
	s_waitcnt vmcnt(12)
	s_cmp_eq_u32 s7, 0
	s_cbranch_scc0 .Lp3_hp0
	v_mov_b32_e32 v128, 0
	v_mov_b32_e32 v129, 0
	v_mov_b32_e32 v130, 0
	v_mov_b32_e32 v131, 0
.Lp3_hp0:
	s_cmp_eq_u32 s7, s8
	s_cbranch_scc0 .Lp3_hn0
	v_mov_b32_e32 v132, 0
	v_mov_b32_e32 v133, 0
	v_mov_b32_e32 v134, 0
	v_mov_b32_e32 v135, 0
; #define UNPACK8(v, f) do { f[0]=lo16(v.x); f[1]=hi16(v.x); f[2]=lo16(v.y); f[3]=hi16(v.y); f[4]=lo16(v.z); f[5]=hi16(v.z); f[6]=lo16(v.w); f[7]=hi16(v.w); } while (0)
; #define PACK8(f) make_uint4(pack2(f[0],f[1]), pack2(f[2],f[3]), pack2(f[4],f[5]), pack2(f[6],f[7]))
; DI float sum8(float v) { v += __shfl_xor(v, 1); v += __shfl_xor(v, 2); v += __shfl_xor(v, 4); return v; }
; DI void phase3(const Params& P) {
;     ...
;       const int col = arr * 512 + lane * 8;
;       uint4 cu = *(const uint4*)(USH + (size_t)m * 1792 + col);
;       uint4 pu = hasp ? *(const uint4*)(USH + (size_t)(m - 1) * 1792 + col) : z4;
;       uint4 nu = hasn ? *(const uint4*)(USH + (size_t)(m + 1) * 1792 + col) : z4;
;       float c8[8], p8[8], n8[8], o8[8]; UNPACK8(cu, c8); UNPACK8(pu, p8); UNPACK8(nu, n8);
; #pragma unroll
;       for (int j = 0; j < 8; ++j) { float mu0 = P.shift_mu[col + j], mu1 = P.shift_mu[1792 + col + j]; o8[j] = c8[j] + mu0 * (p8[j] - c8[j]) + mu1 * (n8[j] - c8[j]); }
;       bf16_t* dst = (bf16_t*)(P.ws + OFF_R + arr * SZ_ARR) + (size_t)m * 512 + lane * 8;
;       *(uint4*)dst = PACK8(o8);
;       if (arr == 1) {
;         float k8[8], ss = 0;
; #pragma unroll
;         for (int j = 0; j < 8; ++j) { k8[j] = o8[j] * P.rw_kk[lane * 8 + j]; ss += k8[j] * k8[j]; }
;         ss = sum8(ss);
;         const float inv = rsqrtf(fmaxf(ss, 1e-24f));
; #pragma unroll
;         for (int j = 0; j < 8; ++j) k8[j] *= inv;
;         *(uint4*)((bf16_t*)(P.ws + OFF_KK) + (size_t)m * 512 + lane * 8) = PACK8(k8);
;       }
.Lp3_hn0:
	v_lshlrev_b32_e32 v180, 16, v124
	v_and_b32_e32 v181, 0xffff0000, v124
	v_lshlrev_b32_e32 v182, 16, v125
	v_and_b32_e32 v183, 0xffff0000, v125
	v_lshlrev_b32_e32 v184, 16, v126
	v_and_b32_e32 v185, 0xffff0000, v126
	v_lshlrev_b32_e32 v186, 16, v127
	v_and_b32_e32 v187, 0xffff0000, v127
	v_lshlrev_b32_e32 v188, 16, v128
	v_and_b32_e32 v189, 0xffff0000, v128
	v_lshlrev_b32_e32 v190, 16, v129
	v_and_b32_e32 v191, 0xffff0000, v129
	v_lshlrev_b32_e32 v192, 16, v130
	v_and_b32_e32 v193, 0xffff0000, v130
	v_lshlrev_b32_e32 v194, 16, v131
	v_and_b32_e32 v195, 0xffff0000, v131
	v_lshlrev_b32_e32 v196, 16, v132
	v_and_b32_e32 v197, 0xffff0000, v132
	v_lshlrev_b32_e32 v198, 16, v133
	v_and_b32_e32 v199, 0xffff0000, v133
	v_lshlrev_b32_e32 v200, 16, v134
	v_and_b32_e32 v201, 0xffff0000, v134
	v_lshlrev_b32_e32 v202, 16, v135
	v_and_b32_e32 v203, 0xffff0000, v135
	v_pk_add_f32 v[188:189], v[188:189], v[180:181] neg_lo:[0,1] neg_hi:[0,1]
	v_pk_add_f32 v[196:197], v[196:197], v[180:181] neg_lo:[0,1] neg_hi:[0,1]
	v_pk_add_f32 v[190:191], v[190:191], v[182:183] neg_lo:[0,1] neg_hi:[0,1]
	v_pk_add_f32 v[198:199], v[198:199], v[182:183] neg_lo:[0,1] neg_hi:[0,1]
	v_pk_add_f32 v[192:193], v[192:193], v[184:185] neg_lo:[0,1] neg_hi:[0,1]
	v_pk_add_f32 v[200:201], v[200:201], v[184:185] neg_lo:[0,1] neg_hi:[0,1]
	v_pk_add_f32 v[194:195], v[194:195], v[186:187] neg_lo:[0,1] neg_hi:[0,1]
	v_pk_add_f32 v[202:203], v[202:203], v[186:187] neg_lo:[0,1] neg_hi:[0,1]
	v_pk_fma_f32 v[210:211], v[16:17], v[188:189], v[180:181]
	v_pk_fma_f32 v[212:213], v[18:19], v[190:191], v[182:183]
	v_pk_fma_f32 v[214:215], v[20:21], v[192:193], v[184:185]
	v_pk_fma_f32 v[216:217], v[22:23], v[194:195], v[186:187]
	v_pk_fma_f32 v[210:211], v[40:41], v[196:197], v[210:211]
	v_pk_fma_f32 v[212:213], v[42:43], v[198:199], v[212:213]
	v_pk_fma_f32 v[214:215], v[44:45], v[200:201], v[214:215]
	v_pk_fma_f32 v[216:217], v[46:47], v[202:203], v[216:217]
	v_cvt_pk_bf16_f32 v204, v210, v211
	v_cvt_pk_bf16_f32 v205, v212, v213
	v_cvt_pk_bf16_f32 v206, v214, v215
	v_cvt_pk_bf16_f32 v207, v216, v217
	global_store_dwordx4 v2, v[204:207], s[22:23]
	s_waitcnt vmcnt(10)
	s_cmp_eq_u32 s7, 0
	s_cbranch_scc0 .Lp3_hp1
	v_mov_b32_e32 v140, 0
	v_mov_b32_e32 v141, 0
	v_mov_b32_e32 v142, 0
	v_mov_b32_e32 v143, 0
.Lp3_hp1:
	s_cmp_eq_u32 s7, s8
	s_cbranch_scc0 .Lp3_hn1
	v_mov_b32_e32 v144, 0
	v_mov_b32_e32 v145, 0
	v_mov_b32_e32 v146, 0
	v_mov_b32_e32 v147, 0
.Lp3_hn1:
	v_lshlrev_b32_e32 v180, 16, v136
	v_and_b32_e32 v181, 0xffff0000, v136
	v_lshlrev_b32_e32 v182, 16, v137
	v_and_b32_e32 v183, 0xffff0000, v137
	v_lshlrev_b32_e32 v184, 16, v138
	v_and_b32_e32 v185, 0xffff0000, v138
	v_lshlrev_b32_e32 v186, 16, v139
	v_and_b32_e32 v187, 0xffff0000, v139
	v_lshlrev_b32_e32 v188, 16, v140
	v_and_b32_e32 v189, 0xffff0000, v140
	v_lshlrev_b32_e32 v190, 16, v141
	v_and_b32_e32 v191, 0xffff0000, v141
	v_lshlrev_b32_e32 v192, 16, v142
	v_and_b32_e32 v193, 0xffff0000, v142
	v_lshlrev_b32_e32 v194, 16, v143
	v_and_b32_e32 v195, 0xffff0000, v143
	v_lshlrev_b32_e32 v196, 16, v144
	v_and_b32_e32 v197, 0xffff0000, v144
	v_lshlrev_b32_e32 v198, 16, v145
	v_and_b32_e32 v199, 0xffff0000, v145
	v_lshlrev_b32_e32 v200, 16, v146
	v_and_b32_e32 v201, 0xffff0000, v146
	v_lshlrev_b32_e32 v202, 16, v147
	v_and_b32_e32 v203, 0xffff0000, v147
	v_pk_add_f32 v[188:189], v[188:189], v[180:181] neg_lo:[0,1] neg_hi:[0,1]
	v_pk_add_f32 v[196:197], v[196:197], v[180:181] neg_lo:[0,1] neg_hi:[0,1]
	v_pk_add_f32 v[190:191], v[190:191], v[182:183] neg_lo:[0,1] neg_hi:[0,1]
	v_pk_add_f32 v[198:199], v[198:199], v[182:183] neg_lo:[0,1] neg_hi:[0,1]
	v_pk_add_f32 v[192:193], v[192:193], v[184:185] neg_lo:[0,1] neg_hi:[0,1]
	v_pk_add_f32 v[200:201], v[200:201], v[184:185] neg_lo:[0,1] neg_hi:[0,1]
	v_pk_add_f32 v[194:195], v[194:195], v[186:187] neg_lo:[0,1] neg_hi:[0,1]
	v_pk_add_f32 v[202:203], v[202:203], v[186:187] neg_lo:[0,1] neg_hi:[0,1]
	v_pk_fma_f32 v[210:211], v[24:25], v[188:189], v[180:181]
	v_pk_fma_f32 v[212:213], v[26:27], v[190:191], v[182:183]
	v_pk_fma_f32 v[214:215], v[28:29], v[192:193], v[184:185]
	v_pk_fma_f32 v[216:217], v[30:31], v[194:195], v[186:187]
	v_pk_fma_f32 v[210:211], v[48:49], v[196:197], v[210:211]
	v_pk_fma_f32 v[212:213], v[50:51], v[198:199], v[212:213]
	v_pk_fma_f32 v[214:215], v[52:53], v[200:201], v[214:215]
	v_pk_fma_f32 v[216:217], v[54:55], v[202:203], v[216:217]
	v_cvt_pk_bf16_f32 v204, v210, v211
	v_cvt_pk_bf16_f32 v205, v212, v213
	v_cvt_pk_bf16_f32 v206, v214, v215
	v_cvt_pk_bf16_f32 v207, v216, v217
	global_store_dwordx4 v2, v[204:207], s[24:25]
	v_pk_mul_f32 v[218:219], v[210:211], v[100:101]
	v_pk_mul_f32 v[220:221], v[212:213], v[102:103]
	v_pk_mul_f32 v[222:223], v[214:215], v[104:105]
	v_pk_mul_f32 v[224:225], v[216:217], v[106:107]
	v_pk_mul_f32 v[226:227], v[218:219], v[218:219]
	v_pk_fma_f32 v[226:227], v[220:221], v[220:221], v[226:227]
	v_pk_fma_f32 v[226:227], v[222:223], v[222:223], v[226:227]
	v_pk_fma_f32 v[226:227], v[224:225], v[224:225], v[226:227]
	v_add_f32_e32 v226, v226, v227
	s_nop 1
	v_add_f32_dpp v226, v226, v226 quad_perm:[1,0,3,2] row_mask:0xf bank_mask:0xf bound_ctrl:1
	s_nop 1
	v_add_f32_dpp v226, v226, v226 quad_perm:[2,3,0,1] row_mask:0xf bank_mask:0xf bound_ctrl:1
	s_nop 1
	v_add_f32_dpp v226, v226, v226 row_half_mirror row_mask:0xf bank_mask:0xf bound_ctrl:1
	v_max_f32_e32 v226, 0x179abe15, v226
	v_rsq_f32_e32 v226, v226
	s_nop 0
	v_pk_mul_f32 v[218:219], v[218:219], v[226:227] op_sel_hi:[1,0]
	v_pk_mul_f32 v[220:221], v[220:221], v[226:227] op_sel_hi:[1,0]
	v_pk_mul_f32 v[222:223], v[222:223], v[226:227] op_sel_hi:[1,0]
	v_pk_mul_f32 v[224:225], v[224:225], v[226:227] op_sel_hi:[1,0]
	v_cvt_pk_bf16_f32 v228, v218, v219
	v_cvt_pk_bf16_f32 v229, v220, v221
	v_cvt_pk_bf16_f32 v230, v222, v223
	v_cvt_pk_bf16_f32 v231, v224, v225
	global_store_dwordx4 v2, v[228:231], s[28:29]
	s_waitcnt vmcnt(9)
	s_cmp_eq_u32 s7, 0
	s_cbranch_scc0 .Lp3_hp2
	v_mov_b32_e32 v152, 0
	v_mov_b32_e32 v153, 0
	v_mov_b32_e32 v154, 0
	v_mov_b32_e32 v155, 0
; DI void phase3(const Params& P) {
;     ...
;       uint4 cu = *(const uint4*)(USH + (size_t)m * 1792 + col);
;       uint4 pu = hasp ? *(const uint4*)(USH + (size_t)(m - 1) * 1792 + col) : z4;
;       uint4 nu = hasn ? *(const uint4*)(USH + (size_t)(m + 1) * 1792 + col) : z4;
;       float c8[8], p8[8], n8[8], o8[8]; UNPACK8(cu, c8); UNPACK8(pu, p8); UNPACK8(nu, n8);
; #pragma unroll
;       for (int j = 0; j < 8; ++j) { float mu0 = P.shift_mu[col + j], mu1 = P.shift_mu[1792 + col + j]; o8[j] = c8[j] + mu0 * (p8[j] - c8[j]) + mu1 * (n8[j] - c8[j]); }
;       bf16_t* dst = (bf16_t*)(P.ws + OFF_R + arr * SZ_ARR) + (size_t)m * 512 + lane * 8;
;       *(uint4*)dst = PACK8(o8);
;       if (arr == 1) {
;         float k8[8], ss = 0;
; #pragma unroll
;         for (int j = 0; j < 8; ++j) { k8[j] = o8[j] * P.rw_kk[lane * 8 + j]; ss += k8[j] * k8[j]; }
;         ss = sum8(ss);
;         const float inv = rsqrtf(fmaxf(ss, 1e-24f));
; #pragma unroll
;         for (int j = 0; j < 8; ++j) k8[j] *= inv;
;         *(uint4*)((bf16_t*)(P.ws + OFF_KK) + (size_t)m * 512 + lane * 8) = PACK8(k8);
;       }
;     }
;     {
;       const int col = 1536 + lane * 4;
;       uint2 cu = *(const uint2*)(USH + (size_t)m * 1792 + col);
;       uint2 pu = hasp ? *(const uint2*)(USH + (size_t)(m - 1) * 1792 + col) : make_uint2(0, 0);
;       uint2 nu = hasn ? *(const uint2*)(USH + (size_t)(m + 1) * 1792 + col) : make_uint2(0, 0);
;       float c4[4] = {lo16(cu.x), hi16(cu.x), lo16(cu.y), hi16(cu.y)}, p4[4] = {lo16(pu.x), hi16(pu.x), lo16(pu.y), hi16(pu.y)}, n4[4] = {lo16(nu.x), hi16(nu.x), lo16(nu.y), hi16(nu.y)}, o4[4];
; #pragma unroll
;       for (int j = 0; j < 4; ++j) { float mu0 = P.shift_mu[col + j], mu1 = P.shift_mu[1792 + col + j]; float o = c4[j] + mu0 * (p4[j] - c4[j]) + mu1 * (n4[j] - c4[j]);
;         if (lane < 32) { float e2 = __expf(2.f * o); o = 1.f - 2.f / (e2 + 1.f); }
;         o4[j] = o; }
;       *(uint2*)((bf16_t*)(P.ws + OFF_LW) + (size_t)m * 256 + lane * 4) = make_uint2(pack2(o4[0], o4[1]), pack2(o4[2], o4[3]));
;     }
;     {
;       float x8[8]; float ss = 0;
;       if (lane < 48) { uint4 u = *(const uint4*)(UMLA + (size_t)m * 672 + lane * 8); UNPACK8(u, x8);
; #pragma unroll
;         for (int j = 0; j < 8; ++j) ss += x8[j] * x8[j]; }
;       ss = wave_sum(ss);
;       const float rstd = rsqrtf(ss * (1.f / 384.f) + 1e-6f);
;       if (lane < 48) {
; #pragma unroll
.Lp3_hp2:
	s_cmp_eq_u32 s7, s8
	s_cbranch_scc0 .Lp3_hn2
	v_mov_b32_e32 v156, 0
	v_mov_b32_e32 v157, 0
	v_mov_b32_e32 v158, 0
	v_mov_b32_e32 v159, 0
.Lp3_hn2:
	v_lshlrev_b32_e32 v180, 16, v148
	v_and_b32_e32 v181, 0xffff0000, v148
	v_lshlrev_b32_e32 v182, 16, v149
	v_and_b32_e32 v183, 0xffff0000, v149
	v_lshlrev_b32_e32 v184, 16, v150
	v_and_b32_e32 v185, 0xffff0000, v150
	v_lshlrev_b32_e32 v186, 16, v151
	v_and_b32_e32 v187, 0xffff0000, v151
	v_lshlrev_b32_e32 v188, 16, v152
	v_and_b32_e32 v189, 0xffff0000, v152
	v_lshlrev_b32_e32 v190, 16, v153
	v_and_b32_e32 v191, 0xffff0000, v153
	v_lshlrev_b32_e32 v192, 16, v154
	v_and_b32_e32 v193, 0xffff0000, v154
	v_lshlrev_b32_e32 v194, 16, v155
	v_and_b32_e32 v195, 0xffff0000, v155
	v_lshlrev_b32_e32 v196, 16, v156
	v_and_b32_e32 v197, 0xffff0000, v156
	v_lshlrev_b32_e32 v198, 16, v157
	v_and_b32_e32 v199, 0xffff0000, v157
	v_lshlrev_b32_e32 v200, 16, v158
	v_and_b32_e32 v201, 0xffff0000, v158
	v_lshlrev_b32_e32 v202, 16, v159
	v_and_b32_e32 v203, 0xffff0000, v159
	v_pk_add_f32 v[188:189], v[188:189], v[180:181] neg_lo:[0,1] neg_hi:[0,1]
	v_pk_add_f32 v[196:197], v[196:197], v[180:181] neg_lo:[0,1] neg_hi:[0,1]
	v_pk_add_f32 v[190:191], v[190:191], v[182:183] neg_lo:[0,1] neg_hi:[0,1]
	v_pk_add_f32 v[198:199], v[198:199], v[182:183] neg_lo:[0,1] neg_hi:[0,1]
	v_pk_add_f32 v[192:193], v[192:193], v[184:185] neg_lo:[0,1] neg_hi:[0,1]
	v_pk_add_f32 v[200:201], v[200:201], v[184:185] neg_lo:[0,1] neg_hi:[0,1]
	v_pk_add_f32 v[194:195], v[194:195], v[186:187] neg_lo:[0,1] neg_hi:[0,1]
	v_pk_add_f32 v[202:203], v[202:203], v[186:187] neg_lo:[0,1] neg_hi:[0,1]
	v_pk_fma_f32 v[210:211], v[32:33], v[188:189], v[180:181]
	v_pk_fma_f32 v[212:213], v[34:35], v[190:191], v[182:183]
	v_pk_fma_f32 v[214:215], v[36:37], v[192:193], v[184:185]
	v_pk_fma_f32 v[216:217], v[38:39], v[194:195], v[186:187]
	v_pk_fma_f32 v[210:211], v[56:57], v[196:197], v[210:211]
	v_pk_fma_f32 v[212:213], v[58:59], v[198:199], v[212:213]
	v_pk_fma_f32 v[214:215], v[60:61], v[200:201], v[214:215]
	v_pk_fma_f32 v[216:217], v[62:63], v[202:203], v[216:217]
	v_cvt_pk_bf16_f32 v204, v210, v211
	v_cvt_pk_bf16_f32 v205, v212, v213
	v_cvt_pk_bf16_f32 v206, v214, v215
	v_cvt_pk_bf16_f32 v207, v216, v217
	global_store_dwordx4 v2, v[204:207], s[26:27]
	s_waitcnt vmcnt(7)
	s_cmp_eq_u32 s7, 0
	s_cbranch_scc0 .Lp3_hpl
	v_mov_b32_e32 v162, 0
	v_mov_b32_e32 v163, 0
.Lp3_hpl:
	s_cmp_eq_u32 s7, s8
	s_cbranch_scc0 .Lp3_hnl
	v_mov_b32_e32 v164, 0
	v_mov_b32_e32 v165, 0
.Lp3_hnl:
	v_lshlrev_b32_e32 v180, 16, v160
	v_and_b32_e32 v181, 0xffff0000, v160
	v_lshlrev_b32_e32 v182, 16, v161
	v_and_b32_e32 v183, 0xffff0000, v161
	v_lshlrev_b32_e32 v188, 16, v162
	v_and_b32_e32 v189, 0xffff0000, v162
	v_lshlrev_b32_e32 v190, 16, v163
	v_and_b32_e32 v191, 0xffff0000, v163
	v_lshlrev_b32_e32 v196, 16, v164
	v_and_b32_e32 v197, 0xffff0000, v164
	v_lshlrev_b32_e32 v198, 16, v165
	v_and_b32_e32 v199, 0xffff0000, v165
	v_pk_add_f32 v[188:189], v[188:189], v[180:181] neg_lo:[0,1] neg_hi:[0,1]
	v_pk_add_f32 v[196:197], v[196:197], v[180:181] neg_lo:[0,1] neg_hi:[0,1]
	v_pk_add_f32 v[190:191], v[190:191], v[182:183] neg_lo:[0,1] neg_hi:[0,1]
	v_pk_add_f32 v[198:199], v[198:199], v[182:183] neg_lo:[0,1] neg_hi:[0,1]
	v_pk_fma_f32 v[210:211], v[88:89], v[188:189], v[180:181]
	v_pk_fma_f32 v[212:213], v[90:91], v[190:191], v[182:183]
	v_pk_fma_f32 v[210:211], v[92:93], v[196:197], v[210:211]
	v_pk_fma_f32 v[212:213], v[94:95], v[198:199], v[212:213]
	v_mul_f32_e32 v218, 0x4038aa3b, v210
	v_mul_f32_e32 v219, 0x4038aa3b, v211
	v_mul_f32_e32 v220, 0x4038aa3b, v212
	v_mul_f32_e32 v221, 0x4038aa3b, v213
	v_exp_f32_e32 v218, v218
	v_exp_f32_e32 v219, v219
	v_exp_f32_e32 v220, v220
	v_exp_f32_e32 v221, v221
	s_nop 0
	v_add_f32_e32 v218, 1.0, v218
	v_add_f32_e32 v219, 1.0, v219
	v_add_f32_e32 v220, 1.0, v220
	v_add_f32_e32 v221, 1.0, v221
	v_rcp_f32_e32 v218, v218
	v_rcp_f32_e32 v219, v219
	v_rcp_f32_e32 v220, v220
	v_rcp_f32_e32 v221, v221
	s_nop 0
	v_fma_f32 v218, v218, -2.0, 1.0
	v_fma_f32 v219, v219, -2.0, 1.0
	v_fma_f32 v220, v220, -2.0, 1.0
	v_fma_f32 v221, v221, -2.0, 1.0
	v_cndmask_b32_e64 v210, v210, v218, s[46:47]
	v_cndmask_b32_e64 v211, v211, v219, s[46:47]
	v_cndmask_b32_e64 v212, v212, v220, s[46:47]
	v_cndmask_b32_e64 v213, v213, v221, s[46:47]
	v_cvt_pk_bf16_f32 v204, v210, v211
	v_cvt_pk_bf16_f32 v205, v212, v213
	global_store_dwordx2 v3, v[204:205], s[30:31]
	s_waitcnt vmcnt(7)
	v_lshlrev_b32_e32 v180, 16, v166
	v_and_b32_e32 v181, 0xffff0000, v166
	v_lshlrev_b32_e32 v182, 16, v167
	v_and_b32_e32 v183, 0xffff0000, v167
	v_lshlrev_b32_e32 v184, 16, v168
	v_and_b32_e32 v185, 0xffff0000, v168
	v_lshlrev_b32_e32 v186, 16, v169
	v_and_b32_e32 v187, 0xffff0000, v169
	v_pk_mul_f32 v[226:227], v[180:181], v[180:181]
	v_pk_fma_f32 v[226:227], v[182:183], v[182:183], v[226:227]
	v_pk_fma_f32 v[226:227], v[184:185], v[184:185], v[226:227]
	v_pk_fma_f32 v[226:227], v[186:187], v[186:187], v[226:227]
	v_add_f32_e32 v226, v226, v227
	v_cndmask_b32_e64 v226, 0, v226, s[44:45]
	s_nop 1
	v_add_f32_dpp v226, v226, v226 quad_perm:[1,0,3,2] row_mask:0xf bank_mask:0xf bound_ctrl:1
	s_nop 1
	v_add_f32_dpp v226, v226, v226 quad_perm:[2,3,0,1] row_mask:0xf bank_mask:0xf bound_ctrl:1
	s_nop 1
	v_add_f32_dpp v226, v226, v226 row_half_mirror row_mask:0xf bank_mask:0xf bound_ctrl:1
	s_nop 1
	v_add_f32_dpp v226, v226, v226 row_mirror row_mask:0xf bank_mask:0xf bound_ctrl:1
	v_mov_b32_e32 v227, v226
	s_nop 1
	v_permlane16_swap_b32_e32 v226, v227
	v_add_f32_e32 v226, v226, v227
	v_mov_b32_e32 v227, v226
	s_nop 1
	v_permlane32_swap_b32_e32 v226, v227
	v_add_f32_e32 v226, v226, v227
	v_mov_b32_e32 v228, 0x358637bd
	v_fmac_f32_e32 v228, 0x3b2aaaab, v226
	v_rsq_f32_e32 v228, v228
	v_pk_mul_f32 v[180:181], v[180:181], v[108:109]
	v_pk_mul_f32 v[182:183], v[182:183], v[110:111]
	v_pk_mul_f32 v[184:185], v[184:185], v[112:113]
	v_pk_mul_f32 v[186:187], v[186:187], v[114:115]
	v_pk_mul_f32 v[180:181], v[180:181], v[228:229] op_sel_hi:[1,0]
	v_pk_mul_f32 v[182:183], v[182:183], v[228:229] op_sel_hi:[1,0]
	v_pk_mul_f32 v[184:185], v[184:185], v[228:229] op_sel_hi:[1,0]
	v_pk_mul_f32 v[186:187], v[186:187], v[228:229] op_sel_hi:[1,0]
	v_cvt_pk_bf16_f32 v204, v180, v181
	v_cvt_pk_bf16_f32 v205, v182, v183
	v_cvt_pk_bf16_f32 v206, v184, v185
	v_cvt_pk_bf16_f32 v207, v186, v187
	s_mov_b64 s[32:33], exec
	s_and_b64 exec, exec, s[44:45]
	global_store_dwordx4 v2, v[204:207], s[34:35]
	s_mov_b64 exec, s[32:33]
	s_waitcnt vmcnt(7)
; #define UNPACK8(v, f) do { f[0]=lo16(v.x); f[1]=hi16(v.x); f[2]=lo16(v.y); f[3]=hi16(v.y); f[4]=lo16(v.z); f[5]=hi16(v.z); f[6]=lo16(v.w); f[7]=hi16(v.w); } while (0)
; #define PACK8(f) make_uint4(pack2(f[0],f[1]), pack2(f[2],f[3]), pack2(f[4],f[5]), pack2(f[6],f[7]))
; DI float wave_sum(float v) { for (int o = 32; o > 0; o >>= 1) v += __shfl_xor(v, o); return v; }
; DI void phase3(const Params& P) {
;     ...
;     {
;       float x8[8]; float ss = 0;
;       if (lane < 32) { uint4 u = *(const uint4*)(UMLA + (size_t)m * 672 + 384 + lane * 8); UNPACK8(u, x8);
; #pragma unroll
;         for (int j = 0; j < 8; ++j) ss += x8[j] * x8[j]; }
;       ss = wave_sum(ss);
;       const float rstd = rsqrtf(ss * (1.f / 256.f) + 1e-6f);
;       if (lane < 32) {
; #pragma unroll
;         for (int j = 0; j < 8; ++j) x8[j] = x8[j] * rstd * P.kv_g[lane * 8 + j];
;         *(uint4*)((bf16_t*)(P.ws + OFF_CKV) + (size_t)m * 256 + lane * 8) = PACK8(x8); }
;     }
;     {
;       float x8[8];
;       const int l4 = lane & 3;
;       uint4 u = *(const uint4*)(UMLA + (size_t)m * 672 + 640 + l4 * 8); UNPACK8(u, x8);
;       const bool lat = m < T_LAT;
;       const float pos = (float)((l4 < 2) ? (t >> 6) : (t & 63));
; #pragma unroll
;       for (int j = 0; j < 8; ++j) {
;         float partner = __shfl_xor(x8[j], 1);
;         if (lat) { float ang = pos * exp2f(-(float)j * (13.287712379549449f / 8.f)); float cs = __cosf(ang), sn = __sinf(ang);
;           x8[j] = (l4 & 1) ? (partner * sn + x8[j] * cs) : (x8[j] * cs - partner * sn); }
;       }
;       if (lane < 4) *(uint4*)((bf16_t*)(P.ws + OFF_KR) + ((size_t)b * LK + kpos) * 32 + lane * 8) = PACK8(x8);
;     }
;   }
	v_lshlrev_b32_e32 v180, 16, v170
	v_and_b32_e32 v181, 0xffff0000, v170
	v_lshlrev_b32_e32 v182, 16, v171
	v_and_b32_e32 v183, 0xffff0000, v171
	v_lshlrev_b32_e32 v184, 16, v172
	v_and_b32_e32 v185, 0xffff0000, v172
	v_lshlrev_b32_e32 v186, 16, v173
	v_and_b32_e32 v187, 0xffff0000, v173
	v_pk_mul_f32 v[226:227], v[180:181], v[180:181]
	v_pk_fma_f32 v[226:227], v[182:183], v[182:183], v[226:227]
	v_pk_fma_f32 v[226:227], v[184:185], v[184:185], v[226:227]
	v_pk_fma_f32 v[226:227], v[186:187], v[186:187], v[226:227]
	v_add_f32_e32 v226, v226, v227
	v_cndmask_b32_e64 v226, 0, v226, s[46:47]
	s_nop 1
	v_add_f32_dpp v226, v226, v226 quad_perm:[1,0,3,2] row_mask:0xf bank_mask:0xf bound_ctrl:1
	s_nop 1
	v_add_f32_dpp v226, v226, v226 quad_perm:[2,3,0,1] row_mask:0xf bank_mask:0xf bound_ctrl:1
	s_nop 1
	v_add_f32_dpp v226, v226, v226 row_half_mirror row_mask:0xf bank_mask:0xf bound_ctrl:1
	s_nop 1
	v_add_f32_dpp v226, v226, v226 row_mirror row_mask:0xf bank_mask:0xf bound_ctrl:1
	v_mov_b32_e32 v227, v226
	s_nop 1
	v_permlane16_swap_b32_e32 v226, v227
	v_add_f32_e32 v226, v226, v227
	v_mov_b32_e32 v227, v226
	s_nop 1
	v_permlane32_swap_b32_e32 v226, v227
	v_add_f32_e32 v226, v226, v227
	v_mov_b32_e32 v228, 0x358637bd
	v_fmac_f32_e32 v228, 0x3b800000, v226
	v_rsq_f32_e32 v228, v228
	v_pk_mul_f32 v[180:181], v[180:181], v[116:117]
	v_pk_mul_f32 v[182:183], v[182:183], v[118:119]
	v_pk_mul_f32 v[184:185], v[184:185], v[120:121]
	v_pk_mul_f32 v[186:187], v[186:187], v[122:123]
	v_pk_mul_f32 v[180:181], v[180:181], v[228:229] op_sel_hi:[1,0]
	v_pk_mul_f32 v[182:183], v[182:183], v[228:229] op_sel_hi:[1,0]
	v_pk_mul_f32 v[184:185], v[184:185], v[228:229] op_sel_hi:[1,0]
	v_pk_mul_f32 v[186:187], v[186:187], v[228:229] op_sel_hi:[1,0]
	v_cvt_pk_bf16_f32 v204, v180, v181
	v_cvt_pk_bf16_f32 v205, v182, v183
	v_cvt_pk_bf16_f32 v206, v184, v185
	v_cvt_pk_bf16_f32 v207, v186, v187
	s_mov_b64 s[32:33], exec
	s_and_b64 exec, exec, s[46:47]
	global_store_dwordx4 v2, v[204:207], s[36:37]
	s_mov_b64 exec, s[32:33]
	s_waitcnt vmcnt(7)
	v_lshlrev_b32_e32 v180, 16, v174
	v_and_b32_e32 v181, 0xffff0000, v174
	v_lshlrev_b32_e32 v182, 16, v175
	v_and_b32_e32 v183, 0xffff0000, v175
	v_lshlrev_b32_e32 v184, 16, v176
	v_and_b32_e32 v185, 0xffff0000, v176
	v_lshlrev_b32_e32 v186, 16, v177
	v_and_b32_e32 v187, 0xffff0000, v177
	s_cmp_lt_u32 s10, 0x4000
	s_cbranch_scc0 .Lp3_norope
	s_lshr_b32 s0, s7, 6
	s_and_b32 s1, s7, 63
	v_mov_b32_e32 v226, s0
	v_mov_b32_e32 v227, s1
	v_cndmask_b32_e64 v226, v227, v226, s[56:57]
	v_cvt_f32_u32_e32 v226, v226
	v_mul_f32_e32 v228, 0.15915494, v226
	v_sin_f32_e32 v229, v228
	v_cos_f32_e32 v230, v228
	v_mov_b32_dpp v231, v180 quad_perm:[1,0,3,2] row_mask:0xf bank_mask:0xf bound_ctrl:1
	v_mul_f32_e32 v231, v229, v231
	v_cndmask_b32_e64 v231, v231, -v231, s[50:51]
	v_fmac_f32_e32 v231, v230, v180
	v_mov_b32_e32 v210, v231
	v_mul_f32_e32 v228, 0x3ea1e89b, v226
	v_mul_f32_e32 v228, 0.15915494, v228
	v_sin_f32_e32 v229, v228
	v_cos_f32_e32 v230, v228
	v_mov_b32_dpp v231, v181 quad_perm:[1,0,3,2] row_mask:0xf bank_mask:0xf bound_ctrl:1
	v_mul_f32_e32 v231, v229, v231
	v_cndmask_b32_e64 v231, v231, -v231, s[50:51]
	v_fmac_f32_e32 v231, v230, v181
	v_mov_b32_e32 v211, v231
	v_mul_f32_e32 v228, 0x3dcccccd, v226
	v_mul_f32_e32 v228, 0.15915494, v228
	v_sin_f32_e32 v229, v228
	v_cos_f32_e32 v230, v228
	v_mov_b32_dpp v231, v182 quad_perm:[1,0,3,2] row_mask:0xf bank_mask:0xf bound_ctrl:1
	v_mul_f32_e32 v231, v229, v231
	v_cndmask_b32_e64 v231, v231, -v231, s[50:51]
	v_fmac_f32_e32 v231, v230, v182
	v_mov_b32_e32 v212, v231
	v_mul_f32_e32 v228, 0x3d0186e3, v226
	v_mul_f32_e32 v228, 0.15915494, v228
	v_sin_f32_e32 v229, v228
	v_cos_f32_e32 v230, v228
	v_mov_b32_dpp v231, v183 quad_perm:[1,0,3,2] row_mask:0xf bank_mask:0xf bound_ctrl:1
	v_mul_f32_e32 v231, v229, v231
	v_cndmask_b32_e64 v231, v231, -v231, s[50:51]
	v_fmac_f32_e32 v231, v230, v183
	v_mov_b32_e32 v213, v231
	v_mul_f32_e32 v228, 0x3c23d70b, v226
	v_mul_f32_e32 v228, 0.15915494, v228
	v_sin_f32_e32 v229, v228
	v_cos_f32_e32 v230, v228
	v_mov_b32_dpp v231, v184 quad_perm:[1,0,3,2] row_mask:0xf bank_mask:0xf bound_ctrl:1
	v_mul_f32_e32 v231, v229, v231
	v_cndmask_b32_e64 v231, v231, -v231, s[50:51]
	v_fmac_f32_e32 v231, v230, v184
	v_mov_b32_e32 v214, v231
	v_mul_f32_e32 v228, 0x3b4f3e39, v226
	v_mul_f32_e32 v228, 0.15915494, v228
	v_sin_f32_e32 v229, v228
	v_cos_f32_e32 v230, v228
	v_mov_b32_dpp v231, v185 quad_perm:[1,0,3,2] row_mask:0xf bank_mask:0xf bound_ctrl:1
	v_mul_f32_e32 v231, v229, v231
	v_cndmask_b32_e64 v231, v231, -v231, s[50:51]
	v_fmac_f32_e32 v231, v230, v185
	v_mov_b32_e32 v215, v231
	v_mul_f32_e32 v228, 0x3a831270, v226
	v_mul_f32_e32 v228, 0.15915494, v228
	v_sin_f32_e32 v229, v228
	v_cos_f32_e32 v230, v228
	v_mov_b32_dpp v231, v186 quad_perm:[1,0,3,2] row_mask:0xf bank_mask:0xf bound_ctrl:1
	v_mul_f32_e32 v231, v229, v231
	v_cndmask_b32_e64 v231, v231, -v231, s[50:51]
	v_fmac_f32_e32 v231, v230, v186
	v_mov_b32_e32 v216, v231
	v_mul_f32_e32 v228, 0x39a5cb61, v226
	v_mul_f32_e32 v228, 0.15915494, v228
	v_sin_f32_e32 v229, v228
	v_cos_f32_e32 v230, v228
	v_mov_b32_dpp v231, v187 quad_perm:[1,0,3,2] row_mask:0xf bank_mask:0xf bound_ctrl:1
	v_mul_f32_e32 v231, v229, v231
	v_cndmask_b32_e64 v231, v231, -v231, s[50:51]
	v_fmac_f32_e32 v231, v230, v187
	v_mov_b32_e32 v217, v231
	s_branch .Lp3_ropedone
.Lp3_norope:
	v_mov_b32_e32 v210, v180
	v_mov_b32_e32 v211, v181
	v_mov_b32_e32 v212, v182
	v_mov_b32_e32 v213, v183
	v_mov_b32_e32 v214, v184
	v_mov_b32_e32 v215, v185
	v_mov_b32_e32 v216, v186
	v_mov_b32_e32 v217, v187
.Lp3_ropedone:
	v_cvt_pk_bf16_f32 v204, v210, v211
	v_cvt_pk_bf16_f32 v205, v212, v213
	v_cvt_pk_bf16_f32 v206, v214, v215
	v_cvt_pk_bf16_f32 v207, v216, v217
	s_mov_b64 s[32:33], exec
	s_and_b64 exec, exec, s[48:49]
	global_store_dwordx4 v2, v[204:207], s[38:39]
	s_mov_b64 exec, s[32:33]
	s_add_u32 s10, s10, s11
	s_cmp_lt_u32 s10, 0x4200
	s_cbranch_scc1 .Lp3_loop
